# cooperative-groups grid sync after phase 0 replaced by a flat counter barrier on a zeroed workspace word
# baseline (speedup 1.0000x reference)
; DI int TIDX() { int t = __builtin_amdgcn_workitem_id_x(); asm volatile("" : "+v"(t)); return t; }
; DI unsigned xb_add(unsigned* q, unsigned v) { return __hip_atomic_fetch_add(q, v, __ATOMIC_RELAXED, __HIP_MEMORY_SCOPE_AGENT); }
; DI unsigned xb_xcc_id() { return (unsigned)__builtin_amdgcn_s_getreg((3 << 11) | 20) & 0xFu; }
; __global__ void __launch_bounds__(256, 2) mega_kernel(Params p_arg) {
;     ...
;   cg::grid_group grid = cg::this_grid();
;   __shared__ unsigned xbst[4];
;   if (TIDX() == 0) (void)xb_add((unsigned*)(p.ws + W_XBAR) + XB_XCNT(xb_xcc_id()), 1u);
;   phase0(p, smem);
;   grid.sync();
.LBB0_183:
	v_bfe_u32 v1, v0, 10, 10
	v_bfe_u32 v0, v0, 20, 10
	v_or3_b32 v2, v160, v1, v0
	v_cmp_eq_u32_e32 vcc, 0, v2
	s_waitcnt lgkmcnt(0)
	s_barrier
	s_and_saveexec_b64 s[2:3], vcc
	s_cbranch_execz .LBB0_193
	buffer_wbl2 sc1
	s_waitcnt vmcnt(0)
	s_load_dwordx2 s[4:5], s[0:1], 0x128
	v_mov_b32_e32 v4, 0x2ac8420
	v_mov_b32_e32 v5, 1
	s_waitcnt lgkmcnt(0)
	global_atomic_add v4, v5, s[4:5]
	s_waitcnt vmcnt(0)
.Lmy_gs_spin:
	s_sleep 1
	global_load_dword v3, v4, s[4:5] sc1
	s_waitcnt vmcnt(0)
	v_readfirstlane_b32 s6, v3
	s_nop 3
	s_cmp_lt_u32 s6, s88
	s_cbranch_scc1 .Lmy_gs_spin
	buffer_inv sc1
